# band attention softmax: s-m via packed v_pk_add (neg broadcast) and row-sum via packed adds (32 sub + 32 add -> 16 + 17)
# baseline (speedup 1.0000x reference)
.LBB0_461:
	v_pk_add_f32 v[146:147], v[146:147], v[50:51] op_sel_hi:[1,0] neg_lo:[0,1] neg_hi:[0,1]
	v_pk_add_f32 v[144:145], v[144:145], v[50:51] op_sel_hi:[1,0] neg_lo:[0,1] neg_hi:[0,1]
	v_pk_add_f32 v[142:143], v[142:143], v[50:51] op_sel_hi:[1,0] neg_lo:[0,1] neg_hi:[0,1]
	v_pk_add_f32 v[140:141], v[140:141], v[50:51] op_sel_hi:[1,0] neg_lo:[0,1] neg_hi:[0,1]
	v_pk_add_f32 v[138:139], v[138:139], v[50:51] op_sel_hi:[1,0] neg_lo:[0,1] neg_hi:[0,1]
	v_pk_add_f32 v[134:135], v[134:135], v[50:51] op_sel_hi:[1,0] neg_lo:[0,1] neg_hi:[0,1]
	v_pk_add_f32 v[130:131], v[130:131], v[50:51] op_sel_hi:[1,0] neg_lo:[0,1] neg_hi:[0,1]
	v_pk_add_f32 v[16:17], v[16:17], v[50:51] op_sel_hi:[1,0] neg_lo:[0,1] neg_hi:[0,1]
	v_pk_add_f32 v[136:137], v[136:137], v[50:51] op_sel_hi:[1,0] neg_lo:[0,1] neg_hi:[0,1]
	v_pk_add_f32 v[132:133], v[132:133], v[50:51] op_sel_hi:[1,0] neg_lo:[0,1] neg_hi:[0,1]
	v_pk_add_f32 v[14:15], v[14:15], v[50:51] op_sel_hi:[1,0] neg_lo:[0,1] neg_hi:[0,1]
	v_pk_add_f32 v[12:13], v[12:13], v[50:51] op_sel_hi:[1,0] neg_lo:[0,1] neg_hi:[0,1]
	v_pk_add_f32 v[10:11], v[10:11], v[50:51] op_sel_hi:[1,0] neg_lo:[0,1] neg_hi:[0,1]
	v_pk_add_f32 v[8:9], v[8:9], v[50:51] op_sel_hi:[1,0] neg_lo:[0,1] neg_hi:[0,1]
	v_pk_add_f32 v[6:7], v[6:7], v[50:51] op_sel_hi:[1,0] neg_lo:[0,1] neg_hi:[0,1]
	v_pk_add_f32 v[4:5], v[4:5], v[50:51] op_sel_hi:[1,0] neg_lo:[0,1] neg_hi:[0,1]
	v_exp_f32_e32 v52, v146
	v_exp_f32_e32 v53, v147
	v_exp_f32_e32 v54, v144
	v_exp_f32_e32 v55, v145
	v_exp_f32_e32 v56, v142
	v_exp_f32_e32 v57, v143
	v_pk_add_f32 v[80:81], v[52:53], v[54:55]
	v_exp_f32_e32 v58, v140
	v_exp_f32_e32 v59, v141
	v_pk_add_f32 v[80:81], v[80:81], v[56:57]
	v_exp_f32_e32 v60, v138
	v_exp_f32_e32 v61, v139
	v_pk_add_f32 v[80:81], v[80:81], v[58:59]
	v_exp_f32_e32 v62, v134
	v_exp_f32_e32 v63, v135
	v_pk_add_f32 v[80:81], v[80:81], v[60:61]
	v_exp_f32_e32 v64, v130
	v_exp_f32_e32 v65, v131
	v_pk_add_f32 v[80:81], v[80:81], v[62:63]
	v_exp_f32_e32 v16, v16
	v_exp_f32_e32 v17, v17
	v_pk_add_f32 v[80:81], v[80:81], v[64:65]
	v_exp_f32_e32 v66, v136
	v_exp_f32_e32 v67, v137
	v_pk_add_f32 v[80:81], v[80:81], v[16:17]
	v_exp_f32_e32 v68, v132
	v_exp_f32_e32 v69, v133
	v_pk_add_f32 v[80:81], v[80:81], v[66:67]
	v_exp_f32_e32 v14, v14
	v_exp_f32_e32 v15, v15
	v_pk_add_f32 v[80:81], v[80:81], v[68:69]
	v_exp_f32_e32 v70, v12
	v_exp_f32_e32 v71, v13
	v_pk_add_f32 v[80:81], v[80:81], v[14:15]
	v_exp_f32_e32 v72, v10
	v_exp_f32_e32 v73, v11
	v_pk_add_f32 v[80:81], v[80:81], v[70:71]
	v_exp_f32_e32 v74, v8
	v_exp_f32_e32 v75, v9
	v_pk_add_f32 v[80:81], v[80:81], v[72:73]
	v_exp_f32_e32 v76, v6
	v_exp_f32_e32 v77, v7
	v_pk_add_f32 v[80:81], v[80:81], v[74:75]
	v_exp_f32_e32 v78, v4
	v_exp_f32_e32 v79, v5
	v_pk_add_f32 v[80:81], v[80:81], v[76:77]
	s_nop 0
	v_pk_add_f32 v[80:81], v[80:81], v[78:79]
	v_add_f32_e32 v80, v80, v81
	v_cvt_pk_bf16_f32 v4, v52, v53
	v_cvt_pk_bf16_f32 v5, v54, v55
	v_cvt_pk_bf16_f32 v6, v56, v57
	v_cvt_pk_bf16_f32 v7, v58, v59
	v_cvt_pk_bf16_f32 v8, v60, v61
	v_cvt_pk_bf16_f32 v9, v62, v63
	v_cvt_pk_bf16_f32 v10, v64, v65
	v_cvt_pk_bf16_f32 v12, v66, v67
	ds_read_b64_tr_b16 v[52:53], v153 offset:9216
	ds_read_b64_tr_b16 v[54:55], v153 offset:9984
	ds_read_b64_tr_b16 v[58:59], v153 offset:10048
	ds_read_b64_tr_b16 v[56:57], v153 offset:9280
	ds_read_b64_tr_b16 v[60:61], v153 offset:12288
	ds_read_b64_tr_b16 v[62:63], v153 offset:13056
	ds_read_b64_tr_b16 v[66:67], v153 offset:13120
	ds_read_b64_tr_b16 v[64:65], v153 offset:12352
	v_fmac_f32_e32 v80, v172, v2
	v_cvt_pk_bf16_f32 v11, v16, v17
	v_cvt_pk_bf16_f32 v13, v68, v69
	v_cvt_pk_bf16_f32 v14, v14, v15
	v_cvt_pk_bf16_f32 v15, v70, v71
	v_cvt_pk_bf16_f32 v68, v72, v73
	v_cvt_pk_bf16_f32 v69, v74, v75
	v_cvt_pk_bf16_f32 v70, v76, v77
	v_cvt_pk_bf16_f32 v71, v78, v79
	s_waitcnt lgkmcnt(6)
	v_mfma_f32_32x32x16_bf16 v[34:49], v[52:55], v[4:7], v[34:49]
	ds_read_b64_tr_b16 v[72:73], v153 offset:15360
	ds_read_b64_tr_b16 v[74:75], v153 offset:16128
	s_waitcnt lgkmcnt(6)
	v_mfma_f32_32x32x16_bf16 v[18:33], v[56:59], v[4:7], v[18:33]
	ds_read_b64_tr_b16 v[52:53], v153 offset:15424
	ds_read_b64_tr_b16 v[54:55], v153 offset:16192
	s_waitcnt lgkmcnt(6)
	v_mfma_f32_32x32x16_bf16 v[34:49], v[60:63], v[8:11], v[34:49]
	ds_read_b64_tr_b16 v[4:5], v153 offset:18432
	ds_read_b64_tr_b16 v[6:7], v153 offset:19200
	s_waitcnt lgkmcnt(6)
	v_mfma_f32_32x32x16_bf16 v[18:33], v[64:67], v[8:11], v[18:33]
	ds_read_b64_tr_b16 v[56:57], v153 offset:18496
	ds_read_b64_tr_b16 v[58:59], v153 offset:19264
	s_waitcnt lgkmcnt(6)
	v_mfma_f32_32x32x16_bf16 v[34:49], v[72:75], v[12:15], v[34:49]
	s_waitcnt lgkmcnt(4)
	v_mfma_f32_32x32x16_bf16 v[18:33], v[52:55], v[12:15], v[18:33]
	s_waitcnt lgkmcnt(2)
	v_mfma_f32_32x32x16_bf16 v[34:49], v[4:7], v[68:71], v[34:49]
	s_waitcnt lgkmcnt(0)
	v_mfma_f32_32x32x16_bf16 v[18:33], v[56:59], v[68:71], v[18:33]
	v_mov_b32_e32 v172, v80
	s_branch .LBB0_463
